# ln1 router reduce-scatter: 30 of the xor-1/2/4/8 exchange steps done with DPP adds instead of ds_bpermute round trips
# baseline (speedup 1.0000x reference)
.Lln1_nopf:
	s_lshl_b64 s[26:27], s[18:19], 10
	s_lshl_b64 s[28:29], s[16:17], 10
	v_lshlrev_b32_e32 v41, 16, v43
	v_lshlrev_b32_e32 v40, 16, v42
	v_and_b32_e32 v93, 0xffff0000, v43
	v_and_b32_e32 v92, 0xffff0000, v42
	v_lshlrev_b32_e32 v49, 16, v45
	v_lshlrev_b32_e32 v48, 16, v44
	v_and_b32_e32 v95, 0xffff0000, v45
	v_and_b32_e32 v94, 0xffff0000, v44
	v_lshlrev_b32_e32 v56, 16, v46
	v_and_b32_e32 v57, 0xffff0000, v46
	v_lshlrev_b32_e32 v58, 16, v47
	v_and_b32_e32 v59, 0xffff0000, v47
	v_pk_add_f32 v[42:43], v[40:41], v[92:93]
	v_lshlrev_b32_e32 v45, 16, v53
	v_lshlrev_b32_e32 v44, 16, v52
	v_and_b32_e32 v97, 0xffff0000, v53
	v_and_b32_e32 v96, 0xffff0000, v52
	v_pk_add_f32 v[46:47], v[48:49], v[94:95]
	v_lshlrev_b32_e32 v53, 16, v55
	v_lshlrev_b32_e32 v52, 16, v54
	v_and_b32_e32 v55, 0xffff0000, v55
	v_and_b32_e32 v54, 0xffff0000, v54
	v_lshlrev_b32_e32 v71, 16, v50
	v_and_b32_e32 v67, 0xffff0000, v50
	v_lshlrev_b32_e32 v69, 16, v51
	v_and_b32_e32 v65, 0xffff0000, v51
	v_add_f32_e32 v68, v56, v57
	v_add_f32_e32 v64, v58, v59
	v_add_f32_e32 v66, v42, v43
	v_pk_add_f32 v[42:43], v[44:45], v[96:97]
	v_pk_add_f32 v[50:51], v[52:53], v[54:55]
	v_pk_add_f32 v[46:47], v[46:47], v[46:47] op_sel:[0,1] op_sel_hi:[1,0]
	v_lshlrev_b32_e32 v60, 16, v62
	v_and_b32_e32 v61, 0xffff0000, v62
	v_lshlrev_b32_e32 v80, 16, v63
	v_and_b32_e32 v81, 0xffff0000, v63
	v_and_b32_e32 v75, 0xffff0000, v72
	v_pk_add_f32 v[62:63], v[68:69], v[64:65]
	v_add_f32_e32 v70, 0, v66
	v_add_f32_e32 v64, v42, v43
	v_mov_b32_e32 v47, v67
	v_pk_add_f32 v[42:43], v[50:51], v[50:51] op_sel:[0,1] op_sel_hi:[1,0]
	v_lshlrev_b32_e32 v79, 16, v72
	v_lshlrev_b32_e32 v77, 16, v73
	v_and_b32_e32 v73, 0xffff0000, v73
	v_add_f32_e32 v76, v60, v61
	v_add_f32_e32 v72, v80, v81
	v_add_f32_e32 v78, 0, v64
	v_pk_add_f32 v[46:47], v[70:71], v[46:47]
	v_mov_b32_e32 v43, v75
	v_pk_add_f32 v[50:51], v[76:77], v[72:73]
	v_pk_add_f32 v[46:47], v[46:47], v[62:63]
	v_pk_add_f32 v[42:43], v[78:79], v[42:43]
	v_add_f32_e32 v46, v46, v47
	v_pk_add_f32 v[42:43], v[42:43], v[50:51]
	v_add_f32_e32 v42, v42, v43
	s_waitcnt lgkmcnt(1)
	v_add_f32_dpp v46, v46, v46 quad_perm:[1,0,3,2] row_mask:0xf bank_mask:0xf
	s_waitcnt lgkmcnt(1)
	v_add_f32_dpp v42, v42, v42 quad_perm:[1,0,3,2] row_mask:0xf bank_mask:0xf
	s_waitcnt lgkmcnt(1)
	v_add_f32_dpp v46, v46, v46 quad_perm:[2,3,0,1] row_mask:0xf bank_mask:0xf
	s_waitcnt lgkmcnt(1)
	v_add_f32_dpp v42, v42, v42 quad_perm:[2,3,0,1] row_mask:0xf bank_mask:0xf
	s_waitcnt lgkmcnt(1)
	v_add_f32_dpp v46, v46, v46 row_half_mirror row_mask:0xf bank_mask:0xf
	s_waitcnt lgkmcnt(1)
	v_add_f32_dpp v42, v42, v42 row_half_mirror row_mask:0xf bank_mask:0xf
	s_waitcnt lgkmcnt(1)
	v_add_f32_dpp v46, v46, v46 row_mirror row_mask:0xf bank_mask:0xf
	s_waitcnt lgkmcnt(1)
	v_add_f32_dpp v42, v42, v42 row_mirror row_mask:0xf bank_mask:0xf
	s_waitcnt lgkmcnt(1)
	v_mov_b32_e32 v47, v46
	s_nop 1
	v_permlane16_swap_b32_e32 v47, v46
	v_add_f32_e32 v46, v46, v47
	s_waitcnt lgkmcnt(1)
	v_mov_b32_e32 v43, v42
	s_nop 1
	v_permlane16_swap_b32_e32 v43, v42
	v_add_f32_e32 v42, v42, v43
	s_waitcnt lgkmcnt(1)
	v_mov_b32_e32 v47, v46
	s_nop 1
	v_permlane32_swap_b32_e32 v47, v46
	v_add_f32_e32 v64, v46, v47
	v_fmac_f32_e32 v92, 0xba800000, v64
	s_waitcnt lgkmcnt(0)
	v_mov_b32_e32 v43, v42
	s_nop 1
	v_permlane32_swap_b32_e32 v43, v42
	v_add_f32_e32 v66, v42, v43
	v_fmac_f32_e32 v93, 0xba800000, v64
	v_fmac_f32_e32 v41, 0xba800000, v64
	v_fmac_f32_e32 v40, 0xba800000, v64
	v_fmac_f32_e32 v96, 0xba800000, v66
	v_fmac_f32_e32 v97, 0xba800000, v66
	v_fmac_f32_e32 v45, 0xba800000, v66
	v_mov_b32_e32 v42, v41
	v_mov_b32_e32 v43, v93
	v_mov_b32_e32 v41, v92
	v_fmac_f32_e32 v44, 0xba800000, v66
	v_pk_mul_f32 v[62:63], v[42:43], v[42:43]
	v_pk_mul_f32 v[92:93], v[40:41], v[40:41]
	v_mov_b32_e32 v46, v45
	v_mov_b32_e32 v47, v97
	v_mov_b32_e32 v45, v96
	v_fmac_f32_e32 v94, 0xba800000, v64
	v_fmac_f32_e32 v95, 0xba800000, v64
	v_fmac_f32_e32 v49, 0xba800000, v64
	v_pk_mov_b32 v[98:99], v[92:93], v[62:63] op_sel:[1,0]
	v_mov_b32_e32 v93, v63
	v_pk_mul_f32 v[62:63], v[46:47], v[46:47]
	v_pk_mul_f32 v[100:101], v[44:45], v[44:45]
	v_fmac_f32_e32 v48, 0xba800000, v64
	v_mov_b32_e32 v50, v49
	v_mov_b32_e32 v51, v95
	v_mov_b32_e32 v49, v94
	v_pk_add_f32 v[92:93], v[92:93], v[98:99]
	v_pk_mov_b32 v[98:99], v[100:101], v[62:63] op_sel:[1,0]
	v_mov_b32_e32 v101, v63
	v_pk_mul_f32 v[94:95], v[50:51], v[50:51]
	v_pk_mul_f32 v[96:97], v[48:49], v[48:49]
	v_pk_add_f32 v[62:63], v[98:99], v[100:101]
	v_fmac_f32_e32 v57, 0xba800000, v64
	v_pk_add_f32 v[98:99], v[62:63], v[62:63] op_sel_hi:[0,1]
	v_pk_mov_b32 v[62:63], v[96:97], v[94:95] op_sel:[1,0]
	v_mov_b32_e32 v97, v95
	v_fmac_f32_e32 v56, 0xba800000, v64
	v_fmac_f32_e32 v59, 0xba800000, v64
	v_fmac_f32_e32 v58, 0xba800000, v64
	v_fmac_f32_e32 v65, 0xba800000, v64
	v_fmac_f32_e32 v69, 0xba800000, v64
	v_fmac_f32_e32 v67, 0xba800000, v64
	v_fmac_f32_e32 v71, 0xba800000, v64
	v_mul_f32_e32 v64, v57, v57
	v_pk_add_f32 v[94:95], v[96:97], v[62:63]
	v_pk_fma_f32 v[100:101], v[56:57], v[56:57], v[64:65] op_sel_hi:[1,1,0]
	v_mul_f32_e32 v64, v59, v59
	v_mul_f32_e32 v68, v71, v71
	v_mul_f32_e32 v70, v67, v67
	v_mul_f32_e32 v72, v69, v69
	v_mul_f32_e32 v74, v65, v65
	v_pk_fma_f32 v[102:103], v[58:59], v[58:59], v[64:65] op_sel_hi:[1,1,0]
	v_pk_add_f32 v[92:93], v[92:93], v[92:93] op_sel:[0,1] op_sel_hi:[1,0]
	v_pk_add_f32 v[94:95], v[94:95], v[94:95] op_sel:[0,1] op_sel_hi:[1,0]
	v_mov_b32_e32 v101, v68
	v_mov_b32_e32 v103, v70
	v_mov_b32_e32 v93, v74
	v_mov_b32_e32 v95, v72
	v_pk_add_f32 v[100:101], v[100:101], v[102:103]
	v_pk_add_f32 v[92:93], v[92:93], v[94:95]
	v_fmac_f32_e32 v54, 0xba800000, v66
	v_pk_add_f32 v[92:93], v[100:101], v[92:93]
	v_fmac_f32_e32 v55, 0xba800000, v66
	v_fmac_f32_e32 v53, 0xba800000, v66
	v_add_f32_e32 v64, v92, v93
	v_fmac_f32_e32 v52, 0xba800000, v66
	v_mov_b32_e32 v62, v53
	v_mov_b32_e32 v63, v55
	v_mov_b32_e32 v53, v54
	v_pk_mul_f32 v[96:97], v[62:63], v[62:63]
	v_pk_mul_f32 v[54:55], v[52:53], v[52:53]
	v_fmac_f32_e32 v60, 0xba800000, v66
	v_pk_mov_b32 v[92:93], v[54:55], v[96:97] op_sel:[1,0]
	v_mov_b32_e32 v55, v97
	v_pk_add_f32 v[54:55], v[92:93], v[54:55]
	v_fmac_f32_e32 v61, 0xba800000, v66
	v_pk_add_f32 v[54:55], v[54:55], v[54:55] op_sel_hi:[0,1]
	s_waitcnt lgkmcnt(0)
	s_nop 0
	v_add_f32_dpp v54, v64, v64 quad_perm:[1,0,3,2] row_mask:0xf bank_mask:0xf
	v_fmac_f32_e32 v80, 0xba800000, v66
	v_fmac_f32_e32 v81, 0xba800000, v66
	v_fmac_f32_e32 v73, 0xba800000, v66
	v_fmac_f32_e32 v77, 0xba800000, v66
	s_waitcnt lgkmcnt(0)
	v_add_f32_dpp v64, v54, v54 quad_perm:[2,3,0,1] row_mask:0xf bank_mask:0xf
	v_mul_f32_e32 v54, v60, v60
	v_pk_fma_f32 v[92:93], v[60:61], v[60:61], v[54:55] op_sel_hi:[1,1,0]
	v_mul_f32_e32 v54, v80, v80
	v_pk_fma_f32 v[94:95], v[80:81], v[80:81], v[54:55] op_sel_hi:[1,1,0]
	s_waitcnt lgkmcnt(0)
	v_add_f32_dpp v54, v64, v64 row_half_mirror row_mask:0xf bank_mask:0xf
	v_fmac_f32_e32 v75, 0xba800000, v66
	v_fmac_f32_e32 v79, 0xba800000, v66
	v_mul_f32_e32 v92, v79, v79
	v_mul_f32_e32 v94, v75, v75
	s_waitcnt lgkmcnt(0)
	v_add_f32_dpp v64, v54, v54 row_mirror row_mask:0xf bank_mask:0xf
	v_mul_f32_e32 v98, v77, v77
	v_mul_f32_e32 v54, v73, v73
	v_pk_add_f32 v[92:93], v[92:93], v[94:95]
	v_pk_add_f32 v[54:55], v[98:99], v[54:55]
	s_waitcnt lgkmcnt(0)
	v_mov_b32_e32 v66, v64
	s_nop 1
	v_permlane16_swap_b32_e32 v66, v64
	v_add_f32_e32 v64, v64, v66
	v_pk_add_f32 v[54:55], v[92:93], v[54:55]
	v_lshl_add_u64 v[96:97], v[38:39], 0, s[20:21]
	v_add_f32_e32 v54, v54, v55
	v_lshl_add_u64 v[98:99], v[38:39], 0, s[22:23]
	s_waitcnt lgkmcnt(0)
	v_mov_b32_e32 v66, v64
	s_nop 1
	v_permlane32_swap_b32_e32 v66, v64
	v_add_f32_e32 v55, v64, v66
	v_fmamk_f32 v55, v55, 0x3a800000, v89
	v_mul_f32_e32 v64, 0x4f800000, v55
	v_cmp_gt_f32_e32 vcc, s24, v55
	v_lshl_add_u64 v[92:93], v[32:33], 0, s[26:27]
	s_waitcnt lgkmcnt(0)
	v_add_f32_dpp v54, v54, v54 quad_perm:[1,0,3,2] row_mask:0xf bank_mask:0xf
	v_cndmask_b32_e32 v55, v55, v64, vcc
	v_sqrt_f32_e32 v64, v55
	v_lshl_add_u64 v[94:95], v[32:33], 0, s[28:29]
	s_waitcnt lgkmcnt(0)
	v_add_f32_dpp v54, v54, v54 quad_perm:[2,3,0,1] row_mask:0xf bank_mask:0xf
	v_add_u32_e32 v68, -1, v64
	v_fma_f32 v70, -v68, v64, v55
	v_cmp_ge_f32_e64 s[12:13], 0, v70
	v_add_u32_e32 v70, 1, v64
	s_waitcnt lgkmcnt(0)
	v_add_f32_dpp v54, v54, v54 row_half_mirror row_mask:0xf bank_mask:0xf
	v_cndmask_b32_e64 v68, v64, v68, s[12:13]
	v_fma_f32 v64, -v70, v64, v55
	v_cmp_lt_f32_e64 s[12:13], 0, v64
	s_waitcnt lgkmcnt(0)
	v_add_f32_dpp v54, v54, v54 row_mirror row_mask:0xf bank_mask:0xf
	v_cndmask_b32_e64 v64, v68, v70, s[12:13]
	v_mul_f32_e32 v68, 0x37800000, v64
	v_cndmask_b32_e32 v64, v64, v68, vcc
	v_cmp_class_f32_e32 vcc, v55, v90
	s_waitcnt lgkmcnt(0)
	v_mov_b32_e32 v66, v54
	s_nop 1
	v_permlane16_swap_b32_e32 v66, v54
	v_add_f32_e32 v54, v54, v66
	v_cndmask_b32_e32 v55, v64, v55, vcc
	v_div_scale_f32 v64, s[12:13], v55, v55, 1.0
	v_rcp_f32_e32 v68, v64
	s_waitcnt lgkmcnt(0)
	v_mov_b32_e32 v66, v54
	s_nop 1
	v_permlane32_swap_b32_e32 v66, v54
	v_add_f32_e32 v54, v54, v66
	v_fmamk_f32 v54, v54, 0x3a800000, v89
	v_mul_f32_e32 v66, 0x4f800000, v54
	v_cmp_gt_f32_e64 s[12:13], s24, v54
	v_fma_f32 v70, -v64, v68, 1.0
	v_fmac_f32_e32 v68, v70, v68
	v_cndmask_b32_e64 v54, v54, v66, s[12:13]
	v_div_scale_f32 v70, vcc, 1.0, v55, 1.0
	v_sqrt_f32_e32 v66, v54
	v_mul_f32_e32 v72, v70, v68
	v_fma_f32 v74, -v64, v72, v70
	v_fmac_f32_e32 v72, v74, v68
	v_fma_f32 v64, -v64, v72, v70
	v_add_u32_e32 v70, -1, v66
	v_fma_f32 v74, -v70, v66, v54
	v_cmp_ge_f32_e64 s[14:15], 0, v74
	v_add_u32_e32 v74, 1, v66
	v_div_fmas_f32 v64, v64, v68, v72
	v_cndmask_b32_e64 v70, v66, v70, s[14:15]
	v_fma_f32 v66, -v74, v66, v54
	v_cmp_lt_f32_e64 s[14:15], 0, v66
	v_div_fixup_f32 v68, v64, v55, 1.0
	v_pk_mul_f32 v[40:41], v[40:41], v[68:69] op_sel_hi:[1,0]
	v_cndmask_b32_e64 v66, v70, v74, s[14:15]
	v_mul_f32_e32 v70, 0x37800000, v66
	v_cndmask_b32_e64 v66, v66, v70, s[12:13]
	v_cmp_class_f32_e64 s[12:13], v54, v90
	v_pk_fma_f32 v[40:41], v[0:1], v[40:41], v[8:9]
	v_pk_mul_f32 v[42:43], v[42:43], v[68:69] op_sel_hi:[1,0]
	v_cndmask_b32_e64 v54, v66, v54, s[12:13]
	v_div_scale_f32 v66, s[12:13], v54, v54, 1.0
	v_rcp_f32_e32 v70, v66
	v_pk_fma_f32 v[42:43], v[2:3], v[42:43], v[10:11]
	v_pk_mul_f32 v[48:49], v[48:49], v[68:69] op_sel_hi:[1,0]
	v_pk_mul_f32 v[56:57], v[68:69], v[56:57] op_sel_hi:[0,1]
	v_fma_f32 v55, -v66, v70, 1.0
	v_fmac_f32_e32 v70, v55, v70
	v_div_scale_f32 v55, vcc, 1.0, v54, 1.0
	v_mul_f32_e32 v64, v55, v70
	v_fma_f32 v72, -v66, v64, v55
	v_fmac_f32_e32 v64, v72, v70
	v_fma_f32 v55, -v66, v64, v55
	v_div_fmas_f32 v55, v55, v70, v64
	v_div_fixup_f32 v70, v55, v54, 1.0
	v_pk_mul_f32 v[44:45], v[44:45], v[70:71] op_sel_hi:[1,0]
	v_mov_b32_e32 v64, 0
	v_pk_mul_f32 v[54:55], v[46:47], v[70:71] op_sel_hi:[1,0]
	v_pk_fma_f32 v[46:47], v[0:1], v[44:45], v[8:9]
	v_cvt_pk_fp8_f32 v64, v40, v41
	v_mov_b32_e32 v66, 0
	v_cvt_pk_fp8_f32 v66, v46, v47
	v_pk_fma_f32 v[44:45], v[2:3], v[54:55], v[10:11]
	v_cvt_pk_fp8_f32 v64, v42, v43 op_sel:[0,0,1]
	v_cvt_pk_bf16_f32 v54, v40, v41
	v_cvt_pk_bf16_f32 v55, v42, v43
	v_cvt_pk_fp8_f32 v66, v44, v45 op_sel:[0,0,1]
	global_store_dwordx2 v[96:97], v[54:55], off
	v_cvt_pk_bf16_f32 v54, v46, v47
	v_cvt_pk_bf16_f32 v55, v44, v45
	global_store_dwordx2 v[98:99], v[54:55], off
	global_store_dword v[92:93], v64, off
	global_store_dword v[94:95], v66, off
	v_pk_mul_f32 v[54:55], v[50:51], v[68:69] op_sel_hi:[1,0]
	v_pk_fma_f32 v[50:51], v[4:5], v[48:49], v[12:13]
	v_pk_mul_f32 v[52:53], v[52:53], v[70:71] op_sel_hi:[1,0]
	v_mov_b32_e32 v64, 0
	v_pk_fma_f32 v[52:53], v[4:5], v[52:53], v[12:13]
	v_cvt_pk_fp8_f32 v64, v50, v51
	v_mov_b32_e32 v66, 0
	v_cvt_pk_fp8_f32 v66, v52, v53
	v_pk_fma_f32 v[54:55], v[6:7], v[54:55], v[14:15]
	v_pk_mul_f32 v[48:49], v[62:63], v[70:71] op_sel_hi:[1,0]
	v_cvt_pk_fp8_f32 v64, v54, v55 op_sel:[0,0,1]
	v_pk_fma_f32 v[48:49], v[6:7], v[48:49], v[14:15]
	v_cvt_pk_bf16_f32 v62, v50, v51
	v_cvt_pk_bf16_f32 v63, v54, v55
	v_cvt_pk_fp8_f32 v66, v48, v49 op_sel:[0,0,1]
	global_store_dwordx2 v[96:97], v[62:63], off offset:512
	v_cvt_pk_bf16_f32 v62, v52, v53
	v_cvt_pk_bf16_f32 v63, v48, v49
	global_store_dwordx2 v[98:99], v[62:63], off offset:512
	global_store_dword v[92:93], v64, off offset:256
	global_store_dword v[94:95], v66, off offset:256
	v_pk_fma_f32 v[62:63], v[16:17], v[56:57], v[24:25]
	v_pk_mul_f32 v[60:61], v[70:71], v[60:61] op_sel_hi:[0,1]
	v_mov_b32_e32 v64, 0
	v_pk_fma_f32 v[60:61], v[16:17], v[60:61], v[24:25]
	v_cvt_pk_fp8_f32 v64, v62, v63
	v_mov_b32_e32 v66, 0
	v_cvt_pk_fp8_f32 v66, v60, v61
	v_pk_mul_f32 v[58:59], v[68:69], v[58:59] op_sel_hi:[0,1]
	v_pk_fma_f32 v[58:59], v[18:19], v[58:59], v[26:27]
	v_pk_mul_f32 v[56:57], v[70:71], v[80:81] op_sel_hi:[0,1]
	v_pk_fma_f32 v[56:57], v[18:19], v[56:57], v[26:27]
	v_cvt_pk_fp8_f32 v64, v58, v59 op_sel:[0,0,1]
	v_cvt_pk_bf16_f32 v80, v62, v63
	v_cvt_pk_bf16_f32 v81, v58, v59
	v_cvt_pk_fp8_f32 v66, v56, v57 op_sel:[0,0,1]
	global_store_dwordx2 v[96:97], v[80:81], off offset:1024
	v_cvt_pk_bf16_f32 v80, v60, v61
	v_cvt_pk_bf16_f32 v81, v56, v57
	global_store_dwordx2 v[98:99], v[80:81], off offset:1024
	global_store_dword v[92:93], v64, off offset:512
	global_store_dword v[94:95], v66, off offset:512
	v_mov_b32_e32 v66, v71
	v_mov_b32_e32 v74, v79
	v_pk_mul_f32 v[66:67], v[68:69], v[66:67] op_sel_hi:[0,1]
	v_mov_b32_e32 v64, v69
	v_pk_mul_f32 v[74:75], v[70:71], v[74:75] op_sel_hi:[0,1]
	v_mov_b32_e32 v72, v77
	v_pk_mul_f32 v[64:65], v[68:69], v[64:65] op_sel_hi:[0,1]
	v_pk_fma_f32 v[68:69], v[20:21], v[66:67], v[28:29]
	v_pk_mul_f32 v[66:67], v[70:71], v[72:73] op_sel_hi:[0,1]
	v_pk_fma_f32 v[70:71], v[20:21], v[74:75], v[28:29]
	v_mov_b32_e32 v74, 0
	v_cvt_pk_fp8_f32 v74, v68, v69
	v_mov_b32_e32 v75, 0
	v_cvt_pk_fp8_f32 v75, v70, v71
	v_pk_fma_f32 v[64:65], v[22:23], v[64:65], v[30:31]
	v_pk_fma_f32 v[66:67], v[22:23], v[66:67], v[30:31]
	v_cvt_pk_fp8_f32 v74, v64, v65 op_sel:[0,0,1]
	v_cvt_pk_bf16_f32 v72, v68, v69
	v_cvt_pk_bf16_f32 v73, v64, v65
	v_cvt_pk_fp8_f32 v75, v66, v67 op_sel:[0,0,1]
	global_store_dwordx2 v[96:97], v[72:73], off offset:1536
	v_cvt_pk_bf16_f32 v72, v70, v71
	v_cvt_pk_bf16_f32 v73, v66, v67
	global_store_dwordx2 v[98:99], v[72:73], off offset:1536
	global_store_dword v[92:93], v74, off offset:768
	global_store_dword v[94:95], v75, off offset:768
	ds_read_b128 v[176:179], v88 offset:0
	ds_read_b128 v[180:183], v88 offset:1024
	ds_read_b128 v[184:187], v88 offset:2048
	ds_read_b128 v[188:191], v88 offset:3072
	ds_read_b128 v[192:195], v88 offset:4096
	ds_read_b128 v[196:199], v88 offset:5120
	ds_read_b128 v[200:203], v88 offset:6144
	ds_read_b128 v[204:207], v88 offset:7168
	s_waitcnt lgkmcnt(4)
	v_pk_mul_f32 v[208:209], v[40:41], v[176:177]
	v_pk_mul_f32 v[210:211], v[46:47], v[176:177]
	v_pk_fma_f32 v[208:209], v[42:43], v[178:179], v[208:209]
	v_pk_fma_f32 v[210:211], v[44:45], v[178:179], v[210:211]
	v_pk_fma_f32 v[208:209], v[50:51], v[180:181], v[208:209]
	v_pk_fma_f32 v[210:211], v[52:53], v[180:181], v[210:211]
	v_pk_fma_f32 v[208:209], v[54:55], v[182:183], v[208:209]
	v_pk_fma_f32 v[210:211], v[48:49], v[182:183], v[210:211]
	v_pk_fma_f32 v[208:209], v[62:63], v[184:185], v[208:209]
	v_pk_fma_f32 v[210:211], v[60:61], v[184:185], v[210:211]
	v_pk_fma_f32 v[208:209], v[58:59], v[186:187], v[208:209]
	v_pk_fma_f32 v[210:211], v[56:57], v[186:187], v[210:211]
	v_pk_fma_f32 v[208:209], v[68:69], v[188:189], v[208:209]
	v_pk_fma_f32 v[210:211], v[70:71], v[188:189], v[210:211]
	v_pk_fma_f32 v[208:209], v[64:65], v[190:191], v[208:209]
	v_pk_fma_f32 v[210:211], v[66:67], v[190:191], v[210:211]
	v_add_f32_e32 v142, v208, v209
	v_add_f32_e32 v143, v210, v211
	ds_read_b128 v[176:179], v88 offset:8192
	ds_read_b128 v[180:183], v88 offset:9216
	ds_read_b128 v[184:187], v88 offset:10240
	ds_read_b128 v[188:191], v88 offset:11264
	s_waitcnt lgkmcnt(4)
	v_pk_mul_f32 v[208:209], v[40:41], v[192:193]
	v_pk_mul_f32 v[210:211], v[46:47], v[192:193]
	v_pk_fma_f32 v[208:209], v[42:43], v[194:195], v[208:209]
	v_pk_fma_f32 v[210:211], v[44:45], v[194:195], v[210:211]
	v_pk_fma_f32 v[208:209], v[50:51], v[196:197], v[208:209]
	v_pk_fma_f32 v[210:211], v[52:53], v[196:197], v[210:211]
	v_pk_fma_f32 v[208:209], v[54:55], v[198:199], v[208:209]
	v_pk_fma_f32 v[210:211], v[48:49], v[198:199], v[210:211]
	v_pk_fma_f32 v[208:209], v[62:63], v[200:201], v[208:209]
	v_pk_fma_f32 v[210:211], v[60:61], v[200:201], v[210:211]
	v_pk_fma_f32 v[208:209], v[58:59], v[202:203], v[208:209]
	v_pk_fma_f32 v[210:211], v[56:57], v[202:203], v[210:211]
	v_pk_fma_f32 v[208:209], v[68:69], v[204:205], v[208:209]
	v_pk_fma_f32 v[210:211], v[70:71], v[204:205], v[210:211]
	v_pk_fma_f32 v[208:209], v[64:65], v[206:207], v[208:209]
	v_pk_fma_f32 v[210:211], v[66:67], v[206:207], v[210:211]
	v_add_f32_e32 v144, v208, v209
	v_add_f32_e32 v145, v210, v211
	ds_read_b128 v[192:195], v88 offset:12288
	ds_read_b128 v[196:199], v88 offset:13312
	ds_read_b128 v[200:203], v88 offset:14336
	ds_read_b128 v[204:207], v88 offset:15360
	s_waitcnt lgkmcnt(4)
	v_pk_mul_f32 v[208:209], v[40:41], v[176:177]
	v_pk_mul_f32 v[210:211], v[46:47], v[176:177]
	v_pk_fma_f32 v[208:209], v[42:43], v[178:179], v[208:209]
	v_pk_fma_f32 v[210:211], v[44:45], v[178:179], v[210:211]
	v_pk_fma_f32 v[208:209], v[50:51], v[180:181], v[208:209]
	v_pk_fma_f32 v[210:211], v[52:53], v[180:181], v[210:211]
	v_pk_fma_f32 v[208:209], v[54:55], v[182:183], v[208:209]
	v_pk_fma_f32 v[210:211], v[48:49], v[182:183], v[210:211]
	v_pk_fma_f32 v[208:209], v[62:63], v[184:185], v[208:209]
	v_pk_fma_f32 v[210:211], v[60:61], v[184:185], v[210:211]
	v_pk_fma_f32 v[208:209], v[58:59], v[186:187], v[208:209]
	v_pk_fma_f32 v[210:211], v[56:57], v[186:187], v[210:211]
	v_pk_fma_f32 v[208:209], v[68:69], v[188:189], v[208:209]
	v_pk_fma_f32 v[210:211], v[70:71], v[188:189], v[210:211]
	v_pk_fma_f32 v[208:209], v[64:65], v[190:191], v[208:209]
	v_pk_fma_f32 v[210:211], v[66:67], v[190:191], v[210:211]
	v_add_f32_e32 v146, v208, v209
	v_add_f32_e32 v147, v210, v211
	ds_read_b128 v[176:179], v88 offset:16384
	ds_read_b128 v[180:183], v88 offset:17408
	ds_read_b128 v[184:187], v88 offset:18432
	ds_read_b128 v[188:191], v88 offset:19456
	s_waitcnt lgkmcnt(4)
	v_pk_mul_f32 v[208:209], v[40:41], v[192:193]
	v_pk_mul_f32 v[210:211], v[46:47], v[192:193]
	v_pk_fma_f32 v[208:209], v[42:43], v[194:195], v[208:209]
	v_pk_fma_f32 v[210:211], v[44:45], v[194:195], v[210:211]
	v_pk_fma_f32 v[208:209], v[50:51], v[196:197], v[208:209]
	v_pk_fma_f32 v[210:211], v[52:53], v[196:197], v[210:211]
	v_pk_fma_f32 v[208:209], v[54:55], v[198:199], v[208:209]
	v_pk_fma_f32 v[210:211], v[48:49], v[198:199], v[210:211]
	v_pk_fma_f32 v[208:209], v[62:63], v[200:201], v[208:209]
	v_pk_fma_f32 v[210:211], v[60:61], v[200:201], v[210:211]
	v_pk_fma_f32 v[208:209], v[58:59], v[202:203], v[208:209]
	v_pk_fma_f32 v[210:211], v[56:57], v[202:203], v[210:211]
	v_pk_fma_f32 v[208:209], v[68:69], v[204:205], v[208:209]
	v_pk_fma_f32 v[210:211], v[70:71], v[204:205], v[210:211]
	v_pk_fma_f32 v[208:209], v[64:65], v[206:207], v[208:209]
	v_pk_fma_f32 v[210:211], v[66:67], v[206:207], v[210:211]
	v_add_f32_e32 v148, v208, v209
	v_add_f32_e32 v149, v210, v211
	ds_read_b128 v[192:195], v88 offset:20480
	ds_read_b128 v[196:199], v88 offset:21504
	ds_read_b128 v[200:203], v88 offset:22528
	ds_read_b128 v[204:207], v88 offset:23552
	s_waitcnt lgkmcnt(4)
	v_pk_mul_f32 v[208:209], v[40:41], v[176:177]
	v_pk_mul_f32 v[210:211], v[46:47], v[176:177]
	v_pk_fma_f32 v[208:209], v[42:43], v[178:179], v[208:209]
	v_pk_fma_f32 v[210:211], v[44:45], v[178:179], v[210:211]
	v_pk_fma_f32 v[208:209], v[50:51], v[180:181], v[208:209]
	v_pk_fma_f32 v[210:211], v[52:53], v[180:181], v[210:211]
	v_pk_fma_f32 v[208:209], v[54:55], v[182:183], v[208:209]
	v_pk_fma_f32 v[210:211], v[48:49], v[182:183], v[210:211]
	v_pk_fma_f32 v[208:209], v[62:63], v[184:185], v[208:209]
	v_pk_fma_f32 v[210:211], v[60:61], v[184:185], v[210:211]
	v_pk_fma_f32 v[208:209], v[58:59], v[186:187], v[208:209]
	v_pk_fma_f32 v[210:211], v[56:57], v[186:187], v[210:211]
	v_pk_fma_f32 v[208:209], v[68:69], v[188:189], v[208:209]
	v_pk_fma_f32 v[210:211], v[70:71], v[188:189], v[210:211]
	v_pk_fma_f32 v[208:209], v[64:65], v[190:191], v[208:209]
	v_pk_fma_f32 v[210:211], v[66:67], v[190:191], v[210:211]
	v_add_f32_e32 v150, v208, v209
	v_add_f32_e32 v151, v210, v211
	ds_read_b128 v[176:179], v88 offset:24576
	ds_read_b128 v[180:183], v88 offset:25600
	ds_read_b128 v[184:187], v88 offset:26624
	ds_read_b128 v[188:191], v88 offset:27648
	s_waitcnt lgkmcnt(4)
	v_pk_mul_f32 v[208:209], v[40:41], v[192:193]
	v_pk_mul_f32 v[210:211], v[46:47], v[192:193]
	v_pk_fma_f32 v[208:209], v[42:43], v[194:195], v[208:209]
	v_pk_fma_f32 v[210:211], v[44:45], v[194:195], v[210:211]
	v_pk_fma_f32 v[208:209], v[50:51], v[196:197], v[208:209]
	v_pk_fma_f32 v[210:211], v[52:53], v[196:197], v[210:211]
	v_pk_fma_f32 v[208:209], v[54:55], v[198:199], v[208:209]
	v_pk_fma_f32 v[210:211], v[48:49], v[198:199], v[210:211]
	v_pk_fma_f32 v[208:209], v[62:63], v[200:201], v[208:209]
	v_pk_fma_f32 v[210:211], v[60:61], v[200:201], v[210:211]
	v_pk_fma_f32 v[208:209], v[58:59], v[202:203], v[208:209]
	v_pk_fma_f32 v[210:211], v[56:57], v[202:203], v[210:211]
	v_pk_fma_f32 v[208:209], v[68:69], v[204:205], v[208:209]
	v_pk_fma_f32 v[210:211], v[70:71], v[204:205], v[210:211]
	v_pk_fma_f32 v[208:209], v[64:65], v[206:207], v[208:209]
	v_pk_fma_f32 v[210:211], v[66:67], v[206:207], v[210:211]
	v_add_f32_e32 v152, v208, v209
	v_add_f32_e32 v153, v210, v211
	ds_read_b128 v[192:195], v88 offset:28672
	ds_read_b128 v[196:199], v88 offset:29696
	ds_read_b128 v[200:203], v88 offset:30720
	ds_read_b128 v[204:207], v88 offset:31744
	s_waitcnt lgkmcnt(4)
	v_pk_mul_f32 v[208:209], v[40:41], v[176:177]
	v_pk_mul_f32 v[210:211], v[46:47], v[176:177]
	v_pk_fma_f32 v[208:209], v[42:43], v[178:179], v[208:209]
	v_pk_fma_f32 v[210:211], v[44:45], v[178:179], v[210:211]
	v_pk_fma_f32 v[208:209], v[50:51], v[180:181], v[208:209]
	v_pk_fma_f32 v[210:211], v[52:53], v[180:181], v[210:211]
	v_pk_fma_f32 v[208:209], v[54:55], v[182:183], v[208:209]
	v_pk_fma_f32 v[210:211], v[48:49], v[182:183], v[210:211]
	v_pk_fma_f32 v[208:209], v[62:63], v[184:185], v[208:209]
	v_pk_fma_f32 v[210:211], v[60:61], v[184:185], v[210:211]
	v_pk_fma_f32 v[208:209], v[58:59], v[186:187], v[208:209]
	v_pk_fma_f32 v[210:211], v[56:57], v[186:187], v[210:211]
	v_pk_fma_f32 v[208:209], v[68:69], v[188:189], v[208:209]
	v_pk_fma_f32 v[210:211], v[70:71], v[188:189], v[210:211]
	v_pk_fma_f32 v[208:209], v[64:65], v[190:191], v[208:209]
	v_pk_fma_f32 v[210:211], v[66:67], v[190:191], v[210:211]
	v_add_f32_e32 v154, v208, v209
	v_add_f32_e32 v155, v210, v211
	ds_read_b128 v[176:179], v88 offset:32768
	ds_read_b128 v[180:183], v88 offset:33792
	ds_read_b128 v[184:187], v88 offset:34816
	ds_read_b128 v[188:191], v88 offset:35840
	s_waitcnt lgkmcnt(4)
	v_pk_mul_f32 v[208:209], v[40:41], v[192:193]
	v_pk_mul_f32 v[210:211], v[46:47], v[192:193]
	v_pk_fma_f32 v[208:209], v[42:43], v[194:195], v[208:209]
	v_pk_fma_f32 v[210:211], v[44:45], v[194:195], v[210:211]
	v_pk_fma_f32 v[208:209], v[50:51], v[196:197], v[208:209]
	v_pk_fma_f32 v[210:211], v[52:53], v[196:197], v[210:211]
	v_pk_fma_f32 v[208:209], v[54:55], v[198:199], v[208:209]
	v_pk_fma_f32 v[210:211], v[48:49], v[198:199], v[210:211]
	v_pk_fma_f32 v[208:209], v[62:63], v[200:201], v[208:209]
	v_pk_fma_f32 v[210:211], v[60:61], v[200:201], v[210:211]
	v_pk_fma_f32 v[208:209], v[58:59], v[202:203], v[208:209]
	v_pk_fma_f32 v[210:211], v[56:57], v[202:203], v[210:211]
	v_pk_fma_f32 v[208:209], v[68:69], v[204:205], v[208:209]
	v_pk_fma_f32 v[210:211], v[70:71], v[204:205], v[210:211]
	v_pk_fma_f32 v[208:209], v[64:65], v[206:207], v[208:209]
	v_pk_fma_f32 v[210:211], v[66:67], v[206:207], v[210:211]
	v_add_f32_e32 v156, v208, v209
	v_add_f32_e32 v157, v210, v211
	ds_read_b128 v[192:195], v88 offset:36864
	ds_read_b128 v[196:199], v88 offset:37888
	ds_read_b128 v[200:203], v88 offset:38912
	ds_read_b128 v[204:207], v88 offset:39936
	s_waitcnt lgkmcnt(4)
	v_pk_mul_f32 v[208:209], v[40:41], v[176:177]
	v_pk_mul_f32 v[210:211], v[46:47], v[176:177]
	v_pk_fma_f32 v[208:209], v[42:43], v[178:179], v[208:209]
	v_pk_fma_f32 v[210:211], v[44:45], v[178:179], v[210:211]
	v_pk_fma_f32 v[208:209], v[50:51], v[180:181], v[208:209]
	v_pk_fma_f32 v[210:211], v[52:53], v[180:181], v[210:211]
	v_pk_fma_f32 v[208:209], v[54:55], v[182:183], v[208:209]
	v_pk_fma_f32 v[210:211], v[48:49], v[182:183], v[210:211]
	v_pk_fma_f32 v[208:209], v[62:63], v[184:185], v[208:209]
	v_pk_fma_f32 v[210:211], v[60:61], v[184:185], v[210:211]
	v_pk_fma_f32 v[208:209], v[58:59], v[186:187], v[208:209]
	v_pk_fma_f32 v[210:211], v[56:57], v[186:187], v[210:211]
	v_pk_fma_f32 v[208:209], v[68:69], v[188:189], v[208:209]
	v_pk_fma_f32 v[210:211], v[70:71], v[188:189], v[210:211]
	v_pk_fma_f32 v[208:209], v[64:65], v[190:191], v[208:209]
	v_pk_fma_f32 v[210:211], v[66:67], v[190:191], v[210:211]
	v_add_f32_e32 v158, v208, v209
	v_add_f32_e32 v159, v210, v211
	ds_read_b128 v[176:179], v88 offset:40960
	ds_read_b128 v[180:183], v88 offset:41984
	ds_read_b128 v[184:187], v88 offset:43008
	ds_read_b128 v[188:191], v88 offset:44032
	s_waitcnt lgkmcnt(4)
	v_pk_mul_f32 v[208:209], v[40:41], v[192:193]
	v_pk_mul_f32 v[210:211], v[46:47], v[192:193]
	v_pk_fma_f32 v[208:209], v[42:43], v[194:195], v[208:209]
	v_pk_fma_f32 v[210:211], v[44:45], v[194:195], v[210:211]
	v_pk_fma_f32 v[208:209], v[50:51], v[196:197], v[208:209]
	v_pk_fma_f32 v[210:211], v[52:53], v[196:197], v[210:211]
	v_pk_fma_f32 v[208:209], v[54:55], v[198:199], v[208:209]
	v_pk_fma_f32 v[210:211], v[48:49], v[198:199], v[210:211]
	v_pk_fma_f32 v[208:209], v[62:63], v[200:201], v[208:209]
	v_pk_fma_f32 v[210:211], v[60:61], v[200:201], v[210:211]
	v_pk_fma_f32 v[208:209], v[58:59], v[202:203], v[208:209]
	v_pk_fma_f32 v[210:211], v[56:57], v[202:203], v[210:211]
	v_pk_fma_f32 v[208:209], v[68:69], v[204:205], v[208:209]
	v_pk_fma_f32 v[210:211], v[70:71], v[204:205], v[210:211]
	v_pk_fma_f32 v[208:209], v[64:65], v[206:207], v[208:209]
	v_pk_fma_f32 v[210:211], v[66:67], v[206:207], v[210:211]
	v_add_f32_e32 v160, v208, v209
	v_add_f32_e32 v161, v210, v211
	ds_read_b128 v[192:195], v88 offset:45056
	ds_read_b128 v[196:199], v88 offset:46080
	ds_read_b128 v[200:203], v88 offset:47104
	ds_read_b128 v[204:207], v88 offset:48128
	s_waitcnt lgkmcnt(4)
	v_pk_mul_f32 v[208:209], v[40:41], v[176:177]
	v_pk_mul_f32 v[210:211], v[46:47], v[176:177]
	v_pk_fma_f32 v[208:209], v[42:43], v[178:179], v[208:209]
	v_pk_fma_f32 v[210:211], v[44:45], v[178:179], v[210:211]
	v_pk_fma_f32 v[208:209], v[50:51], v[180:181], v[208:209]
	v_pk_fma_f32 v[210:211], v[52:53], v[180:181], v[210:211]
	v_pk_fma_f32 v[208:209], v[54:55], v[182:183], v[208:209]
	v_pk_fma_f32 v[210:211], v[48:49], v[182:183], v[210:211]
	v_pk_fma_f32 v[208:209], v[62:63], v[184:185], v[208:209]
	v_pk_fma_f32 v[210:211], v[60:61], v[184:185], v[210:211]
	v_pk_fma_f32 v[208:209], v[58:59], v[186:187], v[208:209]
	v_pk_fma_f32 v[210:211], v[56:57], v[186:187], v[210:211]
	v_pk_fma_f32 v[208:209], v[68:69], v[188:189], v[208:209]
	v_pk_fma_f32 v[210:211], v[70:71], v[188:189], v[210:211]
	v_pk_fma_f32 v[208:209], v[64:65], v[190:191], v[208:209]
	v_pk_fma_f32 v[210:211], v[66:67], v[190:191], v[210:211]
	v_add_f32_e32 v162, v208, v209
	v_add_f32_e32 v163, v210, v211
	ds_read_b128 v[176:179], v88 offset:49152
	ds_read_b128 v[180:183], v88 offset:50176
	ds_read_b128 v[184:187], v88 offset:51200
	ds_read_b128 v[188:191], v88 offset:52224
	s_waitcnt lgkmcnt(4)
	v_pk_mul_f32 v[208:209], v[40:41], v[192:193]
	v_pk_mul_f32 v[210:211], v[46:47], v[192:193]
	v_pk_fma_f32 v[208:209], v[42:43], v[194:195], v[208:209]
	v_pk_fma_f32 v[210:211], v[44:45], v[194:195], v[210:211]
	v_pk_fma_f32 v[208:209], v[50:51], v[196:197], v[208:209]
	v_pk_fma_f32 v[210:211], v[52:53], v[196:197], v[210:211]
	v_pk_fma_f32 v[208:209], v[54:55], v[198:199], v[208:209]
	v_pk_fma_f32 v[210:211], v[48:49], v[198:199], v[210:211]
	v_pk_fma_f32 v[208:209], v[62:63], v[200:201], v[208:209]
	v_pk_fma_f32 v[210:211], v[60:61], v[200:201], v[210:211]
	v_pk_fma_f32 v[208:209], v[58:59], v[202:203], v[208:209]
	v_pk_fma_f32 v[210:211], v[56:57], v[202:203], v[210:211]
	v_pk_fma_f32 v[208:209], v[68:69], v[204:205], v[208:209]
	v_pk_fma_f32 v[210:211], v[70:71], v[204:205], v[210:211]
	v_pk_fma_f32 v[208:209], v[64:65], v[206:207], v[208:209]
	v_pk_fma_f32 v[210:211], v[66:67], v[206:207], v[210:211]
	v_add_f32_e32 v164, v208, v209
	v_add_f32_e32 v165, v210, v211
	ds_read_b128 v[192:195], v88 offset:53248
	ds_read_b128 v[196:199], v88 offset:54272
	ds_read_b128 v[200:203], v88 offset:55296
	ds_read_b128 v[204:207], v88 offset:56320
	s_waitcnt lgkmcnt(4)
	v_pk_mul_f32 v[208:209], v[40:41], v[176:177]
	v_pk_mul_f32 v[210:211], v[46:47], v[176:177]
	v_pk_fma_f32 v[208:209], v[42:43], v[178:179], v[208:209]
	v_pk_fma_f32 v[210:211], v[44:45], v[178:179], v[210:211]
	v_pk_fma_f32 v[208:209], v[50:51], v[180:181], v[208:209]
	v_pk_fma_f32 v[210:211], v[52:53], v[180:181], v[210:211]
	v_pk_fma_f32 v[208:209], v[54:55], v[182:183], v[208:209]
	v_pk_fma_f32 v[210:211], v[48:49], v[182:183], v[210:211]
	v_pk_fma_f32 v[208:209], v[62:63], v[184:185], v[208:209]
	v_pk_fma_f32 v[210:211], v[60:61], v[184:185], v[210:211]
	v_pk_fma_f32 v[208:209], v[58:59], v[186:187], v[208:209]
	v_pk_fma_f32 v[210:211], v[56:57], v[186:187], v[210:211]
	v_pk_fma_f32 v[208:209], v[68:69], v[188:189], v[208:209]
	v_pk_fma_f32 v[210:211], v[70:71], v[188:189], v[210:211]
	v_pk_fma_f32 v[208:209], v[64:65], v[190:191], v[208:209]
	v_pk_fma_f32 v[210:211], v[66:67], v[190:191], v[210:211]
	v_add_f32_e32 v166, v208, v209
	v_add_f32_e32 v167, v210, v211
	ds_read_b128 v[176:179], v88 offset:57344
	ds_read_b128 v[180:183], v88 offset:58368
	ds_read_b128 v[184:187], v88 offset:59392
	ds_read_b128 v[188:191], v88 offset:60416
	s_waitcnt lgkmcnt(4)
	v_pk_mul_f32 v[208:209], v[40:41], v[192:193]
	v_pk_mul_f32 v[210:211], v[46:47], v[192:193]
	v_pk_fma_f32 v[208:209], v[42:43], v[194:195], v[208:209]
	v_pk_fma_f32 v[210:211], v[44:45], v[194:195], v[210:211]
	v_pk_fma_f32 v[208:209], v[50:51], v[196:197], v[208:209]
	v_pk_fma_f32 v[210:211], v[52:53], v[196:197], v[210:211]
	v_pk_fma_f32 v[208:209], v[54:55], v[198:199], v[208:209]
	v_pk_fma_f32 v[210:211], v[48:49], v[198:199], v[210:211]
	v_pk_fma_f32 v[208:209], v[62:63], v[200:201], v[208:209]
	v_pk_fma_f32 v[210:211], v[60:61], v[200:201], v[210:211]
	v_pk_fma_f32 v[208:209], v[58:59], v[202:203], v[208:209]
	v_pk_fma_f32 v[210:211], v[56:57], v[202:203], v[210:211]
	v_pk_fma_f32 v[208:209], v[68:69], v[204:205], v[208:209]
	v_pk_fma_f32 v[210:211], v[70:71], v[204:205], v[210:211]
	v_pk_fma_f32 v[208:209], v[64:65], v[206:207], v[208:209]
	v_pk_fma_f32 v[210:211], v[66:67], v[206:207], v[210:211]
	v_add_f32_e32 v168, v208, v209
	v_add_f32_e32 v169, v210, v211
	ds_read_b128 v[192:195], v88 offset:61440
	ds_read_b128 v[196:199], v88 offset:62464
	ds_read_b128 v[200:203], v88 offset:63488
	ds_read_b128 v[204:207], v88 offset:64512
	s_waitcnt lgkmcnt(4)
	v_pk_mul_f32 v[208:209], v[40:41], v[176:177]
	v_pk_mul_f32 v[210:211], v[46:47], v[176:177]
	v_pk_fma_f32 v[208:209], v[42:43], v[178:179], v[208:209]
	v_pk_fma_f32 v[210:211], v[44:45], v[178:179], v[210:211]
	v_pk_fma_f32 v[208:209], v[50:51], v[180:181], v[208:209]
	v_pk_fma_f32 v[210:211], v[52:53], v[180:181], v[210:211]
	v_pk_fma_f32 v[208:209], v[54:55], v[182:183], v[208:209]
	v_pk_fma_f32 v[210:211], v[48:49], v[182:183], v[210:211]
	v_pk_fma_f32 v[208:209], v[62:63], v[184:185], v[208:209]
	v_pk_fma_f32 v[210:211], v[60:61], v[184:185], v[210:211]
	v_pk_fma_f32 v[208:209], v[58:59], v[186:187], v[208:209]
	v_pk_fma_f32 v[210:211], v[56:57], v[186:187], v[210:211]
	v_pk_fma_f32 v[208:209], v[68:69], v[188:189], v[208:209]
	v_pk_fma_f32 v[210:211], v[70:71], v[188:189], v[210:211]
	v_pk_fma_f32 v[208:209], v[64:65], v[190:191], v[208:209]
	v_pk_fma_f32 v[210:211], v[66:67], v[190:191], v[210:211]
	v_add_f32_e32 v170, v208, v209
	v_add_f32_e32 v171, v210, v211
	s_waitcnt lgkmcnt(0)
	v_pk_mul_f32 v[208:209], v[40:41], v[192:193]
	v_pk_mul_f32 v[210:211], v[46:47], v[192:193]
	v_pk_fma_f32 v[208:209], v[42:43], v[194:195], v[208:209]
	v_pk_fma_f32 v[210:211], v[44:45], v[194:195], v[210:211]
	v_pk_fma_f32 v[208:209], v[50:51], v[196:197], v[208:209]
	v_pk_fma_f32 v[210:211], v[52:53], v[196:197], v[210:211]
	v_pk_fma_f32 v[208:209], v[54:55], v[198:199], v[208:209]
	v_pk_fma_f32 v[210:211], v[48:49], v[198:199], v[210:211]
	v_pk_fma_f32 v[208:209], v[62:63], v[200:201], v[208:209]
	v_pk_fma_f32 v[210:211], v[60:61], v[200:201], v[210:211]
	v_pk_fma_f32 v[208:209], v[58:59], v[202:203], v[208:209]
	v_pk_fma_f32 v[210:211], v[56:57], v[202:203], v[210:211]
	v_pk_fma_f32 v[208:209], v[68:69], v[204:205], v[208:209]
	v_pk_fma_f32 v[210:211], v[70:71], v[204:205], v[210:211]
	v_pk_fma_f32 v[208:209], v[64:65], v[206:207], v[208:209]
	v_pk_fma_f32 v[210:211], v[66:67], v[206:207], v[210:211]
	v_add_f32_e32 v172, v208, v209
	v_add_f32_e32 v173, v210, v211
	v_cndmask_b32_e64 v43, v142, v158, s[0:1]
	v_cndmask_b32_e64 v45, v144, v160, s[0:1]
	v_cndmask_b32_e64 v46, v146, v162, s[0:1]
	v_cndmask_b32_e64 v44, v158, v142, s[0:1]
	s_waitcnt lgkmcnt(2)
	s_nop 0
	v_add_f32_dpp v43, v43, v44 quad_perm:[1,0,3,2] row_mask:0xf bank_mask:0xf
	v_cndmask_b32_e64 v44, v160, v144, s[0:1]
	s_waitcnt lgkmcnt(1)
	s_nop 0
	v_add_f32_dpp v44, v45, v44 quad_perm:[1,0,3,2] row_mask:0xf bank_mask:0xf
	v_cndmask_b32_e64 v45, v162, v146, s[0:1]
	s_waitcnt lgkmcnt(0)
	s_nop 0
	v_add_f32_dpp v45, v46, v45 quad_perm:[1,0,3,2] row_mask:0xf bank_mask:0xf
	v_cndmask_b32_e64 v46, v148, v164, s[0:1]
	v_cndmask_b32_e64 v48, v150, v166, s[0:1]
	v_cndmask_b32_e64 v49, v152, v168, s[0:1]
	v_cndmask_b32_e64 v47, v164, v148, s[0:1]
	s_waitcnt lgkmcnt(2)
	s_nop 0
	v_add_f32_dpp v46, v46, v47 quad_perm:[1,0,3,2] row_mask:0xf bank_mask:0xf
	v_cndmask_b32_e64 v47, v166, v150, s[0:1]
	s_waitcnt lgkmcnt(1)
	s_nop 0
	v_add_f32_dpp v47, v48, v47 quad_perm:[1,0,3,2] row_mask:0xf bank_mask:0xf
	v_cndmask_b32_e64 v48, v168, v152, s[0:1]
	s_waitcnt lgkmcnt(0)
	s_nop 0
	v_add_f32_dpp v48, v49, v48 quad_perm:[1,0,3,2] row_mask:0xf bank_mask:0xf
	v_cndmask_b32_e64 v49, v154, v170, s[0:1]
	v_cndmask_b32_e64 v51, v156, v172, s[0:1]
	v_cndmask_b32_e64 v50, v170, v154, s[0:1]
	v_cndmask_b32_e64 v41, v172, v156, s[0:1]
	s_waitcnt lgkmcnt(1)
	v_add_f32_dpp v49, v49, v50 quad_perm:[1,0,3,2] row_mask:0xf bank_mask:0xf
	v_cndmask_b32_e64 v52, v43, v47, s[4:5]
	s_waitcnt lgkmcnt(0)
	v_add_f32_dpp v41, v51, v41 quad_perm:[1,0,3,2] row_mask:0xf bank_mask:0xf
	v_cndmask_b32_e64 v43, v47, v43, s[4:5]
	v_cndmask_b32_e64 v47, v44, v48, s[4:5]
	v_cndmask_b32_e64 v44, v48, v44, s[4:5]
	v_cndmask_b32_e64 v48, v45, v49, s[4:5]
	v_cndmask_b32_e64 v50, v46, v41, s[4:5]
	v_cndmask_b32_e64 v45, v49, v45, s[4:5]
	s_waitcnt lgkmcnt(3)
	v_add_f32_dpp v43, v52, v43 quad_perm:[2,3,0,1] row_mask:0xf bank_mask:0xf
	s_waitcnt lgkmcnt(2)
	v_add_f32_dpp v45, v48, v45 quad_perm:[2,3,0,1] row_mask:0xf bank_mask:0xf
	v_cndmask_b32_e64 v41, v41, v46, s[4:5]
	s_waitcnt lgkmcnt(1)
	v_add_f32_dpp v44, v47, v44 quad_perm:[2,3,0,1] row_mask:0xf bank_mask:0xf
	s_waitcnt lgkmcnt(0)
	v_add_f32_dpp v41, v50, v41 quad_perm:[2,3,0,1] row_mask:0xf bank_mask:0xf
	v_cndmask_b32_e64 v46, v43, v45, s[6:7]
	v_cndmask_b32_e64 v47, v44, v41, s[6:7]
	v_cndmask_b32_e64 v42, v45, v43, s[6:7]
	v_cndmask_b32_e64 v41, v41, v44, s[6:7]
	v_cndmask_b32_e64 v44, v143, v159, s[0:1]
	s_waitcnt lgkmcnt(1)
	v_add_f32_dpp v42, v46, v42 row_shl:4 row_mask:0xf bank_mask:0x5
	s_nop 1
	v_add_f32_dpp v42, v46, v42 row_shr:4 row_mask:0xf bank_mask:0xa
	v_cndmask_b32_e64 v46, v145, v161, s[0:1]
	s_waitcnt lgkmcnt(1)
	v_add_f32_dpp v41, v47, v41 row_shl:4 row_mask:0xf bank_mask:0x5
	s_nop 1
	v_add_f32_dpp v41, v47, v41 row_shr:4 row_mask:0xf bank_mask:0xa
	v_cndmask_b32_e64 v47, v147, v163, s[0:1]
	v_cndmask_b32_e64 v45, v159, v143, s[0:1]
	s_waitcnt lgkmcnt(2)
	s_nop 0
	v_add_f32_dpp v44, v44, v45 quad_perm:[1,0,3,2] row_mask:0xf bank_mask:0xf
	v_cndmask_b32_e64 v45, v161, v145, s[0:1]
	s_waitcnt lgkmcnt(1)
	s_nop 0
	v_add_f32_dpp v45, v46, v45 quad_perm:[1,0,3,2] row_mask:0xf bank_mask:0xf
	v_cndmask_b32_e64 v46, v163, v147, s[0:1]
	s_waitcnt lgkmcnt(0)
	s_nop 0
	v_add_f32_dpp v46, v47, v46 quad_perm:[1,0,3,2] row_mask:0xf bank_mask:0xf
	v_cndmask_b32_e64 v47, v149, v165, s[0:1]
	v_cndmask_b32_e64 v49, v151, v167, s[0:1]
	v_cndmask_b32_e64 v50, v153, v169, s[0:1]
	v_cndmask_b32_e64 v48, v165, v149, s[0:1]
	s_waitcnt lgkmcnt(2)
	s_nop 0
	v_add_f32_dpp v47, v47, v48 quad_perm:[1,0,3,2] row_mask:0xf bank_mask:0xf
	v_cndmask_b32_e64 v48, v167, v151, s[0:1]
	s_waitcnt lgkmcnt(1)
	s_nop 0
	v_add_f32_dpp v48, v49, v48 quad_perm:[1,0,3,2] row_mask:0xf bank_mask:0xf
	v_cndmask_b32_e64 v49, v169, v153, s[0:1]
	s_waitcnt lgkmcnt(0)
	s_nop 0
	v_add_f32_dpp v49, v50, v49 quad_perm:[1,0,3,2] row_mask:0xf bank_mask:0xf
	v_cndmask_b32_e64 v50, v155, v171, s[0:1]
	v_cndmask_b32_e64 v52, v157, v173, s[0:1]
	v_cndmask_b32_e64 v51, v171, v155, s[0:1]
	v_cndmask_b32_e64 v40, v173, v157, s[0:1]
	v_cndmask_b32_e64 v53, v44, v48, s[4:5]
	s_waitcnt lgkmcnt(1)
	v_add_f32_dpp v50, v50, v51 quad_perm:[1,0,3,2] row_mask:0xf bank_mask:0xf
	s_waitcnt lgkmcnt(0)
	v_add_f32_dpp v40, v52, v40 quad_perm:[1,0,3,2] row_mask:0xf bank_mask:0xf
	v_cndmask_b32_e64 v44, v48, v44, s[4:5]
	v_cndmask_b32_e64 v48, v45, v49, s[4:5]
	v_cndmask_b32_e64 v45, v49, v45, s[4:5]
	v_cndmask_b32_e64 v49, v46, v50, s[4:5]
	v_cndmask_b32_e64 v51, v47, v40, s[4:5]
	v_cndmask_b32_e64 v46, v50, v46, s[4:5]
	v_cndmask_b32_e64 v40, v40, v47, s[4:5]
	s_waitcnt lgkmcnt(3)
	v_add_f32_dpp v44, v53, v44 quad_perm:[2,3,0,1] row_mask:0xf bank_mask:0xf
	s_waitcnt lgkmcnt(2)
	v_add_f32_dpp v45, v48, v45 quad_perm:[2,3,0,1] row_mask:0xf bank_mask:0xf
	s_waitcnt lgkmcnt(1)
	v_add_f32_dpp v46, v49, v46 quad_perm:[2,3,0,1] row_mask:0xf bank_mask:0xf
	s_waitcnt lgkmcnt(0)
	v_add_f32_dpp v40, v51, v40 quad_perm:[2,3,0,1] row_mask:0xf bank_mask:0xf
	v_cndmask_b32_e64 v47, v44, v46, s[6:7]
	v_cndmask_b32_e64 v48, v45, v40, s[6:7]
	v_cndmask_b32_e64 v44, v46, v44, s[6:7]
	v_cndmask_b32_e64 v40, v40, v45, s[6:7]
	v_cndmask_b32_e64 v43, v42, v41, s[8:9]
	s_waitcnt lgkmcnt(1)
	v_add_f32_dpp v44, v47, v44 row_shl:4 row_mask:0xf bank_mask:0x5
	s_nop 1
	v_add_f32_dpp v44, v47, v44 row_shr:4 row_mask:0xf bank_mask:0xa
	s_waitcnt lgkmcnt(0)
	v_add_f32_dpp v40, v48, v40 row_shl:4 row_mask:0xf bank_mask:0x5
	s_nop 1
	v_add_f32_dpp v40, v48, v40 row_shr:4 row_mask:0xf bank_mask:0xa
	v_cndmask_b32_e64 v45, v44, v40, s[8:9]
	v_cndmask_b32_e64 v41, v41, v42, s[8:9]
	v_cndmask_b32_e64 v40, v40, v44, s[8:9]
	s_waitcnt lgkmcnt(1)
	v_add_f32_dpp v41, v43, v41 row_shl:8 row_mask:0xf bank_mask:0x3
	s_nop 1
	v_add_f32_dpp v41, v43, v41 row_shr:8 row_mask:0xf bank_mask:0xc
	ds_bpermute_b32 v42, v86, v41
	s_waitcnt lgkmcnt(1)
	v_add_f32_dpp v40, v45, v40 row_shl:8 row_mask:0xf bank_mask:0x3
	s_nop 1
	v_add_f32_dpp v40, v45, v40 row_shr:8 row_mask:0xf bank_mask:0xc
	ds_bpermute_b32 v43, v86, v40
	s_waitcnt lgkmcnt(1)
	v_add_f32_e32 v41, v41, v42
	ds_bpermute_b32 v42, v87, v41
	s_waitcnt lgkmcnt(1)
	v_add_f32_e32 v40, v40, v43
	ds_bpermute_b32 v43, v87, v40
	s_waitcnt lgkmcnt(1)
	v_add_f32_e32 v41, v41, v42
	ds_bpermute_b32 v42, v82, v41
	s_waitcnt lgkmcnt(1)
	v_add_f32_e32 v40, v40, v43
	ds_bpermute_b32 v43, v82, v40
	s_waitcnt lgkmcnt(1)
	v_max_f32_e32 v42, v42, v42
	v_max_f32_e32 v42, v41, v42
	s_waitcnt lgkmcnt(0)
	v_max_f32_e32 v43, v43, v43
	ds_bpermute_b32 v44, v83, v42
	v_max_f32_e32 v43, v40, v43
	ds_bpermute_b32 v45, v83, v43
	s_waitcnt lgkmcnt(1)
	v_max_f32_e32 v44, v44, v44
	v_max_f32_e32 v42, v42, v44
	s_waitcnt lgkmcnt(0)
	v_max_f32_e32 v44, v45, v45
	v_max_f32_e32 v43, v43, v44
	ds_bpermute_b32 v45, v84, v42
	ds_bpermute_b32 v44, v84, v43
	s_waitcnt lgkmcnt(1)
	v_max_f32_e32 v45, v45, v45
	s_waitcnt lgkmcnt(0)
	v_max_f32_e32 v44, v44, v44
	v_max_f32_e32 v42, v42, v45
	v_max_f32_e32 v43, v43, v44
	ds_bpermute_b32 v45, v85, v42
	ds_bpermute_b32 v44, v85, v43
	s_waitcnt lgkmcnt(1)
	v_max_f32_e32 v45, v45, v45
	s_waitcnt lgkmcnt(0)
	v_max_f32_e32 v44, v44, v44
	v_max_f32_e32 v42, v42, v45
	v_max_f32_e32 v43, v43, v44
	v_sub_f32_e32 v41, v41, v42
	v_sub_f32_e32 v40, v40, v43
	v_mul_f32_e32 v41, 0x3fb8aa3b, v41
	v_mul_f32_e32 v40, 0x3fb8aa3b, v40
	v_exp_f32_e32 v41, v41
	v_exp_f32_e32 v40, v40
	ds_bpermute_b32 v42, v82, v41
	ds_bpermute_b32 v43, v82, v40
	s_waitcnt lgkmcnt(1)
	v_add_f32_e32 v42, v41, v42
	s_waitcnt lgkmcnt(0)
	v_add_f32_e32 v43, v40, v43
	ds_bpermute_b32 v44, v83, v42
	ds_bpermute_b32 v45, v83, v43
	s_waitcnt lgkmcnt(1)
	v_add_f32_e32 v42, v42, v44
	s_waitcnt lgkmcnt(0)
	v_add_f32_e32 v44, v43, v45
	ds_bpermute_b32 v43, v84, v42
	ds_bpermute_b32 v45, v84, v44
	s_waitcnt lgkmcnt(1)
	v_add_f32_e32 v43, v42, v43
	s_waitcnt lgkmcnt(0)
	v_add_f32_e32 v42, v44, v45
	ds_bpermute_b32 v45, v85, v43
	ds_bpermute_b32 v44, v85, v42
	s_and_saveexec_b64 s[12:13], s[10:11]
	s_cbranch_execz .LBB0_801
	s_waitcnt lgkmcnt(1)
	v_add_f32_e32 v43, v43, v45
	v_div_scale_f32 v45, s[14:15], v43, v43, v41
	v_rcp_f32_e32 v46, v45
	s_waitcnt lgkmcnt(0)
	v_add_f32_e32 v44, v42, v44
	v_fma_f32 v42, -v45, v46, 1.0
	v_fmac_f32_e32 v46, v42, v46
	v_div_scale_f32 v42, vcc, v41, v43, v41
	v_mul_f32_e32 v47, v42, v46
	v_fma_f32 v48, -v45, v47, v42
	v_fmac_f32_e32 v47, v48, v46
	v_fma_f32 v42, -v45, v47, v42
	v_div_scale_f32 v45, s[14:15], v44, v44, v40
	v_div_fmas_f32 v42, v42, v46, v47
	v_rcp_f32_e32 v46, v45
	v_div_fixup_f32 v41, v42, v43, v41
	v_lshl_add_u64 v[42:43], s[18:19], 2, v[34:35]
	global_store_dword v[42:43], v41, off
	v_fma_f32 v41, -v45, v46, 1.0
	v_fmac_f32_e32 v46, v41, v46
	v_div_scale_f32 v41, vcc, v40, v44, v40
	v_mul_f32_e32 v42, v41, v46
	v_fma_f32 v43, -v45, v42, v41
	v_fmac_f32_e32 v42, v43, v46
	v_fma_f32 v41, -v45, v42, v41
	v_div_fmas_f32 v41, v41, v46, v42
	v_div_fixup_f32 v42, v41, v44, v40
	v_lshl_add_u64 v[40:41], s[16:17], 2, v[34:35]
	global_store_dword v[40:41], v42, off
	s_branch .LBB0_801
